# attention: one static s_setprio 1 for waves 0-3 (per-segment flips removed); fully-masked tiles skip softmax VALU; P6 epilogue relu without self-max; rotary position prefetch
# speedup vs baseline: 1.0266x; 1.0040x over previous
.Lrot_entry:
	s_mov_b64 s[12:13], s[94:95]
	v_or_b32_e32 v0, s70, v203
	s_mov_b32 s0, 0x200000
	s_mov_b64 s[12:13], s[94:95]
	v_cmp_gt_i32_e32 vcc, s0, v0
	s_and_saveexec_b64 s[18:19], vcc
	s_cbranch_execz .LBB0_138
	v_and_b32_e32 v1, 31, v209
	v_sub_u32_e32 v1, 0, v1
	s_mov_b32 s0, 0x979a371
	v_cvt_f64_i32_e32 v[2:3], v1
	s_mov_b32 s1, 0x3fda934f
	v_mul_f64 v[2:3], v[2:3], s[0:1]
	v_rndne_f64_e32 v[4:5], v[2:3]
	s_mov_b32 s0, 0x3b39803f
	v_add_f64 v[6:7], v[2:3], -v[4:5]
	s_mov_b32 s1, 0x3c7abc9e
	v_mul_f64 v[8:9], v[6:7], s[0:1]
	s_mov_b32 s0, 0xfefa39ef
	s_mov_b32 s1, 0x3fe62e42
	v_fmac_f64_e32 v[8:9], s[0:1], v[6:7]
	s_mov_b32 s0, 0x6a5dcb37
	v_mov_b32_e32 v6, 0xfca7ab0c
	v_mov_b32_e32 v7, 0x3e928af3
	s_mov_b32 s1, 0x3e5ade15
	v_fmac_f64_e32 v[6:7], s[0:1], v[8:9]
	v_mov_b32_e32 v10, 0x623fde64
	v_mov_b32_e32 v11, 0x3ec71dee
	v_fmac_f64_e32 v[10:11], v[8:9], v[6:7]
	v_mov_b32_e32 v6, 0x7c89e6b0
	v_mov_b32_e32 v7, 0x3efa0199
	v_fmac_f64_e32 v[6:7], v[8:9], v[10:11]
	v_mov_b32_e32 v10, 0x14761f6e
	v_mov_b32_e32 v11, 0x3f2a01a0
	v_fmac_f64_e32 v[10:11], v[8:9], v[6:7]
	v_mov_b32_e32 v6, 0x1852b7b0
	v_mov_b32_e32 v7, 0x3f56c16c
	v_fmac_f64_e32 v[6:7], v[8:9], v[10:11]
	v_mov_b32_e32 v10, 0x11122322
	v_mov_b32_e32 v11, 0x3f811111
	v_fmac_f64_e32 v[10:11], v[8:9], v[6:7]
	v_mov_b32_e32 v6, 0x555502a1
	v_mov_b32_e32 v7, 0x3fa55555
	v_fmac_f64_e32 v[6:7], v[8:9], v[10:11]
	v_mov_b32_e32 v10, 0x55555511
	v_mov_b32_e32 v11, 0x3fc55555
	v_fmac_f64_e32 v[10:11], v[8:9], v[6:7]
	v_mov_b32_e32 v6, 11
	v_mov_b32_e32 v7, 0x3fe00000
	s_mov_b32 s0, 0
	v_fmac_f64_e32 v[6:7], v[8:9], v[10:11]
	s_mov_b32 s1, 0x40900000
	v_fma_f64 v[6:7], v[8:9], v[6:7], 1.0
	v_cmp_nlt_f64_e32 vcc, s[0:1], v[2:3]
	s_mov_b32 s0, 0
	v_fma_f64 v[6:7], v[8:9], v[6:7], 1.0
	v_cvt_i32_f64_e32 v1, v[4:5]
	s_mov_b32 s1, 0xc090cc00
	v_ldexp_f64 v[4:5], v[6:7], v1
	v_mov_b32_e32 v1, 0x7ff00000
	v_cmp_ngt_f64_e64 s[0:1], s[0:1], v[2:3]
	v_cndmask_b32_e32 v1, v1, v5, vcc
	s_and_b64 vcc, s[0:1], vcc
	s_lshl_b32 s22, s30, 8
	v_cndmask_b32_e64 v3, 0, v1, s[0:1]
	v_cndmask_b32_e32 v2, 0, v4, vcc
	v_ashrrev_i32_e32 v1, 31, v0
	v_cvt_f32_f64_e32 v6, v[2:3]
	v_lshl_add_u64 v[2:3], v[0:1], 2, s[58:59]
	s_mov_b64 s[0:1], 0x3a800000
	s_ashr_i32 s23, s22, 31
	s_mov_b32 s26, 0x6dc9c883
	s_mov_b32 s36, 0x54442d18
	v_lshl_add_u64 v[2:3], v[2:3], 0, s[0:1]
	s_lshl_b64 s[10:11], s[22:23], 2
	s_mov_b64 s[24:25], 0
	s_mov_b32 s27, 0x3fc45f30
	s_mov_b32 s37, 0x401921fb
	s_brev_b32 s23, 18
	s_mov_b32 s34, 0xfe5163ab
	v_mov_b32_e32 v5, 0
	s_mov_b32 s35, 0x3c439041
	s_mov_b32 s40, 0xdb629599
	s_mov_b32 s41, 0xf534ddc0
	s_mov_b32 s42, 0xfc2757d1
	s_mov_b32 s43, 0x4e441529
	s_mov_b32 s44, 0xa2f9836e
	s_mov_b32 s45, 0x3fc90fda
	s_mov_b32 s46, 0x3f22f983
	s_mov_b32 s47, 0xbfc90fda
	v_mov_b32_e32 v1, 0x3c0881c4
	v_mov_b32_e32 v7, 0xbab64f3b
	s_brev_b32 s48, 1
	s_movk_i32 s49, 0x1f8
	s_mov_b32 s50, 0x1fffff
	v_not_b32_e32 v8, 63
	v_not_b32_e32 v9, 31
	v_mov_b32_e32 v10, 0x7fc00000
	v_readlane_b32 s82, v244, 2
	v_readlane_b32 s83, v244, 3
	v_ashrrev_i32_e32 v32, 5, v0
	v_mov_b32_e32 v33, 0
	s_nop 1
	v_lshl_add_u64 v[32:33], v[32:33], 2, s[82:83]
	global_load_dword v30, v[32:33], off
	s_waitcnt vmcnt(0)
	s_branch .LBB0_130

.LBB0_130:
	v_readlane_b32 s80, v244, 0
	v_readlane_b32 s82, v244, 2
	v_readlane_b32 s83, v244, 3
	v_readlane_b32 s81, v244, 1
	v_readlane_b32 s84, v244, 4
	v_add_u32_e32 v31, s22, v0
	v_ashrrev_i32_e32 v32, 5, v31
	v_min_u32_e32 v32, 0xffff, v32
	v_mov_b32_e32 v33, 0
	v_lshl_add_u64 v[32:33], v[32:33], 2, s[82:83]
	s_waitcnt vmcnt(2)
	v_mov_b32_e32 v4, v30
	global_load_dword v30, v[32:33], off
	v_readlane_b32 s85, v244, 5
	v_readlane_b32 s86, v244, 6
	v_readlane_b32 s87, v244, 7
	v_readlane_b32 s88, v244, 8
	v_readlane_b32 s89, v244, 9
	v_readlane_b32 s90, v244, 10
	v_readlane_b32 s91, v244, 11
	v_readlane_b32 s92, v244, 12
	v_readlane_b32 s93, v244, 13
	v_readlane_b32 s94, v244, 14
	v_readlane_b32 s95, v244, 15
	v_cvt_f32_i32_e32 v4, v4
	v_mul_f32_e32 v4, v6, v4
	v_cvt_f64_f32_e32 v[12:13], v4
	v_mul_f64 v[14:15], v[12:13], s[26:27]
	v_rndne_f64_e32 v[14:15], v[14:15]
	v_fma_f64 v[12:13], v[12:13], s[26:27], -v[14:15]
	v_mul_f64 v[12:13], v[12:13], s[36:37]
	v_cvt_f32_f64_e32 v11, v[12:13]
	v_and_b32_e32 v12, 0x7fffffff, v11
	v_lshrrev_b32_e32 v4, 23, v12
	v_and_b32_e32 v13, 0x7fffff, v12
	v_cmp_nlt_f32_e64 s[8:9], |v11|, s23
	v_add_u32_e32 v14, 0xffffff88, v4
	v_or_b32_e32 v13, 0x800000, v13
	s_and_saveexec_b64 s[0:1], s[8:9]
	s_xor_b64 s[38:39], exec, s[0:1]
	s_cbranch_execz .LBB0_132
	v_cmp_lt_u32_e32 vcc, 63, v14
	v_mad_u64_u32 v[16:17], s[6:7], v13, s34, 0
	s_nop 0
	v_cndmask_b32_e32 v4, 0, v8, vcc
	v_add_u32_e32 v4, v4, v14
	v_cmp_lt_u32_e64 s[0:1], 31, v4
	s_nop 1
	v_cndmask_b32_e64 v15, 0, v9, s[0:1]
	v_add_u32_e32 v4, v15, v4
	v_cmp_lt_u32_e64 s[4:5], 31, v4
	s_nop 1
	v_cndmask_b32_e64 v15, 0, v9, s[4:5]
	v_add_u32_e32 v15, v15, v4
	v_mov_b32_e32 v4, v17
	v_mad_u64_u32 v[18:19], s[6:7], v13, s35, v[4:5]
	v_mov_b32_e32 v4, v19
	v_mad_u64_u32 v[20:21], s[6:7], v13, s40, v[4:5]
	v_mov_b32_e32 v4, v21
	v_mad_u64_u32 v[22:23], s[6:7], v13, s41, v[4:5]
	v_mov_b32_e32 v4, v23
	v_mad_u64_u32 v[24:25], s[6:7], v13, s42, v[4:5]
	v_mov_b32_e32 v4, v25
	v_mad_u64_u32 v[26:27], s[6:7], v13, s43, v[4:5]
	v_mov_b32_e32 v4, v27
	v_mad_u64_u32 v[28:29], s[6:7], v13, s44, v[4:5]
	v_cndmask_b32_e32 v17, v26, v22, vcc
	v_cndmask_b32_e32 v4, v28, v24, vcc
	v_cndmask_b32_e32 v21, v29, v26, vcc
	v_cndmask_b32_e64 v19, v4, v17, s[0:1]
	v_cndmask_b32_e64 v4, v21, v4, s[0:1]
	v_cndmask_b32_e32 v21, v24, v20, vcc
	v_cndmask_b32_e64 v17, v17, v21, s[0:1]
	v_sub_u32_e32 v23, 32, v15
	v_cmp_eq_u32_e64 s[6:7], 0, v15
	v_cndmask_b32_e32 v15, v22, v18, vcc
	v_cndmask_b32_e64 v4, v4, v19, s[4:5]
	v_cndmask_b32_e64 v19, v19, v17, s[4:5]
	v_cndmask_b32_e64 v18, v21, v15, s[0:1]
	v_alignbit_b32 v24, v4, v19, v23
	v_cndmask_b32_e64 v17, v17, v18, s[4:5]
	v_cndmask_b32_e64 v4, v24, v4, s[6:7]
	v_alignbit_b32 v21, v19, v17, v23
	v_cndmask_b32_e32 v16, v20, v16, vcc
	v_cndmask_b32_e64 v19, v21, v19, s[6:7]
	v_bfe_u32 v24, v4, 29, 1
	v_cndmask_b32_e64 v15, v15, v16, s[0:1]
	v_alignbit_b32 v21, v4, v19, 30
	v_sub_u32_e32 v25, 0, v24
	v_cndmask_b32_e64 v15, v18, v15, s[4:5]
	v_xor_b32_e32 v21, v21, v25
	v_alignbit_b32 v16, v17, v15, v23
	v_cndmask_b32_e64 v16, v16, v17, s[6:7]
	v_ffbh_u32_e32 v18, v21
	v_alignbit_b32 v17, v19, v16, 30
	v_min_u32_e32 v18, 32, v18
	v_alignbit_b32 v15, v16, v15, 30
	v_xor_b32_e32 v17, v17, v25
	v_sub_u32_e32 v19, 31, v18
	v_xor_b32_e32 v15, v15, v25
	v_alignbit_b32 v20, v21, v17, v19
	v_alignbit_b32 v15, v17, v15, v19
	v_alignbit_b32 v16, v20, v15, 9
	v_ffbh_u32_e32 v17, v16
	v_min_u32_e32 v17, 32, v17
	v_lshrrev_b32_e32 v22, 29, v4
	v_not_b32_e32 v19, v17
	v_alignbit_b32 v15, v16, v15, v19
	v_lshlrev_b32_e32 v16, 31, v22
	v_or_b32_e32 v19, 0x33000000, v16
	v_add_lshl_u32 v17, v17, v18, 23
	v_lshrrev_b32_e32 v15, 9, v15
	v_sub_u32_e32 v17, v19, v17
	v_or_b32_e32 v16, 0.5, v16
	v_lshlrev_b32_e32 v18, 23, v18
	v_or_b32_e32 v15, v17, v15
	v_lshrrev_b32_e32 v17, 9, v20
	v_sub_u32_e32 v16, v16, v18
	v_or_b32_e32 v16, v17, v16
	v_mul_f32_e32 v17, 0x3fc90fda, v16
	v_fma_f32 v18, v16, s45, -v17
	v_fmac_f32_e32 v18, 0x33a22168, v16
	v_fmac_f32_e32 v18, 0x3fc90fda, v15
	v_lshrrev_b32_e32 v4, 30, v4
	v_add_f32_e32 v16, v17, v18
	v_add_u32_e32 v15, v24, v4

.LBB0_487:
	v_readfirstlane_b32 s100, v209
	s_nop 1
	s_bitcmp0_b32 s100, 8
	s_cbranch_scc0 .Lattprio_skip
	s_setprio 1

.LBB0_492:
	ds_read_b128 v[66:69], v197 offset:0
	ds_read_b128 v[70:73], v197 offset:0x4000
	ds_read_b128 v[158:161], v198 offset:0
	ds_read_b128 v[162:165], v198 offset:0x4000
	ds_read_b128 v[166:169], v199 offset:0
	ds_read_b128 v[216:219], v199 offset:0x4000
	ds_read_b128 v[220:223], v200 offset:0
	ds_read_b128 v[224:227], v200 offset:0x4000
	s_waitcnt lgkmcnt(6)
	s_waitcnt vmcnt(14)
	v_mfma_f32_32x32x16_bf16 v[82:97], v[66:69], v[98:101], 0
	v_mfma_f32_32x32x16_bf16 v[66:81], v[70:73], v[98:101], 0
	ds_read_b128 v[228:231], v201 offset:0
	ds_read_b128 v[232:235], v201 offset:0x4000
	s_waitcnt lgkmcnt(6)
	s_waitcnt vmcnt(13)
	v_mfma_f32_32x32x16_bf16 v[82:97], v[158:161], v[102:105], v[82:97]
	v_mfma_f32_32x32x16_bf16 v[66:81], v[162:165], v[102:105], v[66:81]
	ds_read_b128 v[158:161], v202 offset:0
	ds_read_b128 v[162:165], v202 offset:0x4000
	s_waitcnt lgkmcnt(6)
	s_waitcnt vmcnt(12)
	v_mfma_f32_32x32x16_bf16 v[82:97], v[166:169], v[106:109], v[82:97]
	v_mfma_f32_32x32x16_bf16 v[66:81], v[216:219], v[106:109], v[66:81]
	ds_read_b128 v[166:169], v204 offset:0
	ds_read_b128 v[216:219], v204 offset:0x4000
	s_waitcnt lgkmcnt(6)
	s_waitcnt vmcnt(11)
	v_mfma_f32_32x32x16_bf16 v[82:97], v[220:223], v[110:113], v[82:97]
	v_mfma_f32_32x32x16_bf16 v[66:81], v[224:227], v[110:113], v[66:81]
	ds_read_b128 v[220:223], v205 offset:0
	ds_read_b128 v[224:227], v205 offset:0x4000
	s_waitcnt lgkmcnt(6)
	s_waitcnt vmcnt(10)
	v_mfma_f32_32x32x16_bf16 v[82:97], v[228:231], v[114:117], v[82:97]
	v_mfma_f32_32x32x16_bf16 v[66:81], v[232:235], v[114:117], v[66:81]
	ds_read_b128 v[228:231], v197 offset:0x100
	ds_read_b128 v[232:235], v197 offset:0x4100
	s_waitcnt lgkmcnt(6)
	s_waitcnt vmcnt(9)
	v_mfma_f32_32x32x16_bf16 v[82:97], v[158:161], v[118:121], v[82:97]
	v_mfma_f32_32x32x16_bf16 v[66:81], v[162:165], v[118:121], v[66:81]
	ds_read_b128 v[158:161], v198 offset:0x100
	ds_read_b128 v[162:165], v198 offset:0x4100
	s_waitcnt lgkmcnt(6)
	s_waitcnt vmcnt(8)
	v_mfma_f32_32x32x16_bf16 v[82:97], v[166:169], v[122:125], v[82:97]
	v_mfma_f32_32x32x16_bf16 v[66:81], v[216:219], v[122:125], v[66:81]
	ds_read_b128 v[166:169], v199 offset:0x100
	ds_read_b128 v[216:219], v199 offset:0x4100
	s_waitcnt lgkmcnt(6)
	s_waitcnt vmcnt(7)
	v_mfma_f32_32x32x16_bf16 v[82:97], v[220:223], v[126:129], v[82:97]
	v_mfma_f32_32x32x16_bf16 v[66:81], v[224:227], v[126:129], v[66:81]
	ds_read_b128 v[220:223], v200 offset:0x100
	ds_read_b128 v[224:227], v200 offset:0x4100
	s_waitcnt lgkmcnt(6)
	s_waitcnt vmcnt(6)
	v_mfma_f32_32x32x16_bf16 v[82:97], v[228:231], v[130:133], v[82:97]
	v_mfma_f32_32x32x16_bf16 v[66:81], v[232:235], v[130:133], v[66:81]
	s_waitcnt lgkmcnt(4)
	s_waitcnt vmcnt(5)
	v_mfma_f32_32x32x16_bf16 v[82:97], v[158:161], v[134:137], v[82:97]
	v_mfma_f32_32x32x16_bf16 v[66:81], v[162:165], v[134:137], v[66:81]
	s_waitcnt lgkmcnt(2)
	s_waitcnt vmcnt(4)
	v_mfma_f32_32x32x16_bf16 v[82:97], v[166:169], v[138:141], v[82:97]
	v_mfma_f32_32x32x16_bf16 v[66:81], v[216:219], v[138:141], v[66:81]
	s_waitcnt lgkmcnt(0)
	s_waitcnt vmcnt(3)
	v_mfma_f32_32x32x16_bf16 v[82:97], v[220:223], v[142:145], v[82:97]
	v_mfma_f32_32x32x16_bf16 v[66:81], v[224:227], v[142:145], v[66:81]
	s_sub_i32 s101, s86, 158
	s_cmp_gt_i32 s101, s65
	s_cbranch_scc0 .Lnoskip1
	s_nop 7
	s_nop 4
	v_mov_b32_e32 v66, 0
	v_mov_b32_e32 v67, 0
	v_mov_b32_e32 v68, 0
	v_mov_b32_e32 v69, 0
	v_mov_b32_e32 v70, 0
	v_mov_b32_e32 v71, 0
	v_mov_b32_e32 v72, 0
	v_mov_b32_e32 v73, 0
	v_mov_b32_e32 v74, 0
	v_mov_b32_e32 v75, 0
	v_mov_b32_e32 v76, 0
	v_mov_b32_e32 v77, 0
	v_mov_b32_e32 v78, 0
	v_mov_b32_e32 v79, 0
	v_mov_b32_e32 v80, 0
	v_mov_b32_e32 v81, 0
	v_mov_b32_e32 v213, 0
	v_mov_b32_e32 v214, 0
	v_mov_b32_e32 v212, 1.0
	s_branch .LBB0_498
.Lnoskip1:
	s_sub_i32 s4, s86, 64
	s_cmp_le_i32 s4, s65
	s_cbranch_scc1 .LBB0_494
	v_cmp_gt_u32_e32 vcc, 2.0, v181
	v_add_u32_e32 v0, 0xbfffffe0, v181
	s_nop 4
	v_cndmask_b32_e32 v82, v210, v82, vcc
	v_cmp_lt_u32_e32 vcc, s35, v0
	v_add_u32_e32 v0, 0xbfffffff, v181
	s_nop 0
	v_cndmask_b32_e32 v66, v210, v66, vcc
	v_cmp_lt_u32_e32 vcc, s35, v0
	v_add_u32_e32 v0, 0xbfffffdf, v181
	s_nop 0
	v_cndmask_b32_e32 v83, v210, v83, vcc
	v_cmp_lt_u32_e32 vcc, s35, v0
	v_add_u32_e32 v0, 0xbffffffe, v181
	s_nop 0
	v_cndmask_b32_e32 v67, v210, v67, vcc
	v_cmp_lt_u32_e32 vcc, s35, v0
	v_add_u32_e32 v0, 0xbfffffde, v181
	s_nop 0
	v_cndmask_b32_e32 v84, v210, v84, vcc
	v_cmp_lt_u32_e32 vcc, s35, v0
	v_add_u32_e32 v0, 0xbffffffd, v181
	s_nop 0
	v_cndmask_b32_e32 v68, v210, v68, vcc
	v_cmp_lt_u32_e32 vcc, s35, v0
	v_add_u32_e32 v0, 0xbfffffdd, v181
	s_nop 0
	v_cndmask_b32_e32 v85, v210, v85, vcc
	v_cmp_lt_u32_e32 vcc, s35, v0
	v_add_u32_e32 v0, 0xbffffff8, v181
	s_nop 0
	v_cndmask_b32_e32 v69, v210, v69, vcc
	v_cmp_lt_u32_e32 vcc, s35, v0
	v_add_u32_e32 v0, 0xbfffffd8, v181
	s_nop 0
	v_cndmask_b32_e32 v86, v210, v86, vcc
	v_cmp_lt_u32_e32 vcc, s35, v0
	v_add_u32_e32 v0, 0xbffffff7, v181
	s_nop 0
	v_cndmask_b32_e32 v70, v210, v70, vcc
	v_cmp_lt_u32_e32 vcc, s35, v0
	v_add_u32_e32 v0, 0xbfffffd7, v181
	s_nop 0
	v_cndmask_b32_e32 v87, v210, v87, vcc
	v_cmp_lt_u32_e32 vcc, s35, v0
	v_add_u32_e32 v0, 0xbffffff6, v181
	s_nop 0
	v_cndmask_b32_e32 v71, v210, v71, vcc
	v_cmp_lt_u32_e32 vcc, s35, v0
	v_add_u32_e32 v0, 0xbfffffd6, v181
	s_nop 0
	v_cndmask_b32_e32 v88, v210, v88, vcc
	v_cmp_lt_u32_e32 vcc, s35, v0
	v_add_u32_e32 v0, 0xbffffff5, v181
	s_nop 0
	v_cndmask_b32_e32 v72, v210, v72, vcc
	v_cmp_lt_u32_e32 vcc, s35, v0
	v_add_u32_e32 v0, 0xbfffffd5, v181
	s_nop 0
	v_cndmask_b32_e32 v89, v210, v89, vcc
	v_cmp_lt_u32_e32 vcc, s35, v0
	v_add_u32_e32 v0, 0xbffffff0, v181
	s_nop 0
	v_cndmask_b32_e32 v73, v210, v73, vcc
	v_cmp_lt_u32_e32 vcc, s35, v0
	v_add_u32_e32 v0, 0xbfffffd0, v181
	s_nop 0
	v_cndmask_b32_e32 v90, v210, v90, vcc
	v_cmp_lt_u32_e32 vcc, s35, v0
	v_add_u32_e32 v0, 0xbfffffef, v181
	s_nop 0
	v_cndmask_b32_e32 v74, v210, v74, vcc
	v_cmp_lt_u32_e32 vcc, s35, v0
	v_add_u32_e32 v0, 0xbfffffcf, v181
	s_nop 0
	v_cndmask_b32_e32 v91, v210, v91, vcc
	v_cmp_lt_u32_e32 vcc, s35, v0
	v_add_u32_e32 v0, 0xbfffffee, v181
	s_nop 0
	v_cndmask_b32_e32 v75, v210, v75, vcc
	v_cmp_lt_u32_e32 vcc, s35, v0
	v_add_u32_e32 v0, 0xbfffffce, v181
	s_nop 0
	v_cndmask_b32_e32 v92, v210, v92, vcc
	v_cmp_lt_u32_e32 vcc, s35, v0
	v_add_u32_e32 v0, 0xbfffffed, v181
	s_nop 0
	v_cndmask_b32_e32 v76, v210, v76, vcc
	v_cmp_lt_u32_e32 vcc, s35, v0
	v_add_u32_e32 v0, 0xbfffffcd, v181
	s_nop 0
	v_cndmask_b32_e32 v93, v210, v93, vcc
	v_cmp_lt_u32_e32 vcc, s35, v0
	v_add_u32_e32 v0, 0xbfffffe8, v181
	s_nop 0
	v_cndmask_b32_e32 v77, v210, v77, vcc
	v_cmp_lt_u32_e32 vcc, s35, v0
	v_add_u32_e32 v0, 0xbfffffc8, v181
	s_nop 0
	v_cndmask_b32_e32 v94, v210, v94, vcc
	v_cmp_lt_u32_e32 vcc, s35, v0
	v_add_u32_e32 v0, 0xbfffffe7, v181
	s_nop 0
	v_cndmask_b32_e32 v78, v210, v78, vcc
	v_cmp_lt_u32_e32 vcc, s35, v0
	v_add_u32_e32 v0, 0xbfffffc7, v181
	s_nop 0
	v_cndmask_b32_e32 v95, v210, v95, vcc
	v_cmp_lt_u32_e32 vcc, s35, v0
	v_add_u32_e32 v0, 0xbfffffe6, v181
	s_nop 0
	v_cndmask_b32_e32 v79, v210, v79, vcc
	v_cmp_lt_u32_e32 vcc, s35, v0
	v_add_u32_e32 v0, 0xbfffffc6, v181
	s_nop 0
	v_cndmask_b32_e32 v96, v210, v96, vcc
	v_cmp_lt_u32_e32 vcc, s35, v0
	v_add_u32_e32 v0, 0xbfffffe5, v181
	s_nop 0
	v_cndmask_b32_e32 v80, v210, v80, vcc
	v_cmp_lt_u32_e32 vcc, s35, v0
	v_add_u32_e32 v0, 0xbfffffc5, v181
	s_nop 0
	v_cndmask_b32_e32 v97, v210, v97, vcc
	v_cmp_lt_u32_e32 vcc, s35, v0
	s_nop 1
	v_cndmask_b32_e32 v81, v210, v81, vcc

.LBB0_513:
.LBB0_514:
	s_lshl_b32 s18, s25, 14
	v_add_u32_e32 v0, s18, v195
	ds_read_b64_tr_b16 v[82:83], v0 offset:0
	ds_read_b64_tr_b16 v[84:85], v0 offset:0x800
	ds_read_b64_tr_b16 v[86:87], v0 offset:0x1000
	ds_read_b64_tr_b16 v[88:89], v0 offset:0x1800
	ds_read_b64_tr_b16 v[90:91], v0 offset:0x2000
	ds_read_b64_tr_b16 v[92:93], v0 offset:0x2800
	ds_read_b64_tr_b16 v[94:95], v0 offset:0x3000
	ds_read_b64_tr_b16 v[96:97], v0 offset:0x3800
	ds_read_b64_tr_b16 v[158:159], v0 offset:0x200
	ds_read_b64_tr_b16 v[160:161], v0 offset:0xa00
	ds_read_b64_tr_b16 v[162:163], v0 offset:0x1200
	ds_read_b64_tr_b16 v[164:165], v0 offset:0x1a00
	ds_read_b64_tr_b16 v[166:167], v0 offset:0x2200
	ds_read_b64_tr_b16 v[168:169], v0 offset:0x2a00
	ds_read_b64_tr_b16 v[216:217], v0 offset:0x3200
	ds_read_b64_tr_b16 v[218:219], v0 offset:0x3a00
	s_waitcnt lgkmcnt(8)
	s_mov_b64 s[10:11], -1
	v_mfma_f32_32x32x16_bf16 v[50:65], v[66:69], v[82:85], v[50:65]
	v_mfma_f32_32x32x16_bf16 v[50:65], v[70:73], v[86:89], v[50:65]
	v_mfma_f32_32x32x16_bf16 v[50:65], v[74:77], v[90:93], v[50:65]
	v_mfma_f32_32x32x16_bf16 v[50:65], v[78:81], v[94:97], v[50:65]
	ds_read_b64_tr_b16 v[82:83], v0 offset:0x400
	ds_read_b64_tr_b16 v[84:85], v0 offset:0xc00
	ds_read_b64_tr_b16 v[86:87], v0 offset:0x1400
	ds_read_b64_tr_b16 v[88:89], v0 offset:0x1c00
	ds_read_b64_tr_b16 v[90:91], v0 offset:0x2400
	ds_read_b64_tr_b16 v[92:93], v0 offset:0x2c00
	ds_read_b64_tr_b16 v[94:95], v0 offset:0x3400
	ds_read_b64_tr_b16 v[96:97], v0 offset:0x3c00
	s_waitcnt lgkmcnt(8)
	v_mfma_f32_32x32x16_bf16 v[34:49], v[66:69], v[158:161], v[34:49]
	v_mfma_f32_32x32x16_bf16 v[34:49], v[70:73], v[162:165], v[34:49]
	v_mfma_f32_32x32x16_bf16 v[34:49], v[74:77], v[166:169], v[34:49]
	v_mfma_f32_32x32x16_bf16 v[34:49], v[78:81], v[216:219], v[34:49]
	ds_read_b64_tr_b16 v[158:159], v0 offset:0x600
	ds_read_b64_tr_b16 v[160:161], v0 offset:0xe00
	ds_read_b64_tr_b16 v[162:163], v0 offset:0x1600
	ds_read_b64_tr_b16 v[164:165], v0 offset:0x1e00
	ds_read_b64_tr_b16 v[166:167], v0 offset:0x2600
	ds_read_b64_tr_b16 v[168:169], v0 offset:0x2e00
	ds_read_b64_tr_b16 v[216:217], v0 offset:0x3600
	ds_read_b64_tr_b16 v[218:219], v0 offset:0x3e00
	s_waitcnt lgkmcnt(8)
	v_mfma_f32_32x32x16_bf16 v[18:33], v[66:69], v[82:85], v[18:33]
	v_mfma_f32_32x32x16_bf16 v[18:33], v[70:73], v[86:89], v[18:33]
	v_mfma_f32_32x32x16_bf16 v[18:33], v[74:77], v[90:93], v[18:33]
	v_mfma_f32_32x32x16_bf16 v[18:33], v[78:81], v[94:97], v[18:33]
	s_waitcnt lgkmcnt(0)
	v_mfma_f32_32x32x16_bf16 v[2:17], v[66:69], v[158:161], v[2:17]
	v_mfma_f32_32x32x16_bf16 v[2:17], v[70:73], v[162:165], v[2:17]
	v_mfma_f32_32x32x16_bf16 v[2:17], v[74:77], v[166:169], v[2:17]
	v_mfma_f32_32x32x16_bf16 v[2:17], v[78:81], v[216:219], v[2:17]
	s_and_b64 vcc, exec, s[36:37]
	s_cbranch_vccz .LBB0_531
	s_andn2_b64 vcc, exec, s[78:79]
	s_cbranch_vccnz .LBB0_521
	s_xor_b64 s[68:69], s[72:73], -1
	s_and_b64 vcc, exec, s[68:69]
	s_cbranch_vccz .LBB0_518
	s_waitcnt vmcnt(0)
	s_mov_b64 s[10:11], 0

.LBB0_533:
	ds_read_b128 v[66:69], v197 offset:0x8000
	ds_read_b128 v[70:73], v197 offset:0xc000
	s_waitcnt vmcnt(1)
	ds_read_b128 v[146:149], v198 offset:0x8000
	ds_read_b128 v[150:153], v198 offset:0xc000
	s_waitcnt vmcnt(0)
	ds_read_b128 v[154:157], v199 offset:0x8000
	ds_read_b128 v[216:219], v199 offset:0xc000
	ds_read_b128 v[220:223], v200 offset:0x8000
	ds_read_b128 v[224:227], v200 offset:0xc000
	s_waitcnt lgkmcnt(6)
	v_mfma_f32_32x32x16_bf16 v[82:97], v[66:69], v[98:101], 0
	v_mfma_f32_32x32x16_bf16 v[66:81], v[70:73], v[98:101], 0
	ds_read_b128 v[228:231], v201 offset:0x8000
	ds_read_b128 v[232:235], v201 offset:0xc000
	s_waitcnt lgkmcnt(6)
	v_mfma_f32_32x32x16_bf16 v[82:97], v[146:149], v[102:105], v[82:97]
	v_mfma_f32_32x32x16_bf16 v[66:81], v[150:153], v[102:105], v[66:81]
	ds_read_b128 v[146:149], v202 offset:0x8000
	ds_read_b128 v[150:153], v202 offset:0xc000
	s_waitcnt lgkmcnt(6)
	v_mfma_f32_32x32x16_bf16 v[82:97], v[154:157], v[106:109], v[82:97]
	v_mfma_f32_32x32x16_bf16 v[66:81], v[216:219], v[106:109], v[66:81]
	ds_read_b128 v[154:157], v204 offset:0x8000
	ds_read_b128 v[216:219], v204 offset:0xc000
	s_waitcnt lgkmcnt(6)
	v_mfma_f32_32x32x16_bf16 v[82:97], v[220:223], v[110:113], v[82:97]
	v_mfma_f32_32x32x16_bf16 v[66:81], v[224:227], v[110:113], v[66:81]
	ds_read_b128 v[220:223], v205 offset:0x8000
	ds_read_b128 v[224:227], v205 offset:0xc000
	s_waitcnt lgkmcnt(6)
	v_mfma_f32_32x32x16_bf16 v[82:97], v[228:231], v[114:117], v[82:97]
	v_mfma_f32_32x32x16_bf16 v[66:81], v[232:235], v[114:117], v[66:81]
	ds_read_b128 v[228:231], v197 offset:0x8100
	ds_read_b128 v[232:235], v197 offset:0xc100
	s_waitcnt lgkmcnt(6)
	v_mfma_f32_32x32x16_bf16 v[82:97], v[146:149], v[118:121], v[82:97]
	v_mfma_f32_32x32x16_bf16 v[66:81], v[150:153], v[118:121], v[66:81]
	ds_read_b128 v[146:149], v198 offset:0x8100
	ds_read_b128 v[150:153], v198 offset:0xc100
	s_waitcnt lgkmcnt(6)
	v_mfma_f32_32x32x16_bf16 v[82:97], v[154:157], v[122:125], v[82:97]
	v_mfma_f32_32x32x16_bf16 v[66:81], v[216:219], v[122:125], v[66:81]
	ds_read_b128 v[154:157], v199 offset:0x8100
	ds_read_b128 v[216:219], v199 offset:0xc100
	s_waitcnt lgkmcnt(6)
	v_mfma_f32_32x32x16_bf16 v[82:97], v[220:223], v[126:129], v[82:97]
	v_mfma_f32_32x32x16_bf16 v[66:81], v[224:227], v[126:129], v[66:81]
	ds_read_b128 v[220:223], v200 offset:0x8100
	ds_read_b128 v[224:227], v200 offset:0xc100
	s_waitcnt lgkmcnt(6)
	v_mfma_f32_32x32x16_bf16 v[82:97], v[228:231], v[130:133], v[82:97]
	v_mfma_f32_32x32x16_bf16 v[66:81], v[232:235], v[130:133], v[66:81]
	s_waitcnt lgkmcnt(4)
	v_mfma_f32_32x32x16_bf16 v[82:97], v[146:149], v[134:137], v[82:97]
	v_mfma_f32_32x32x16_bf16 v[66:81], v[150:153], v[134:137], v[66:81]
	s_waitcnt lgkmcnt(2)
	v_mfma_f32_32x32x16_bf16 v[82:97], v[154:157], v[138:141], v[82:97]
	v_mfma_f32_32x32x16_bf16 v[66:81], v[216:219], v[138:141], v[66:81]
	s_waitcnt lgkmcnt(0)
	v_mfma_f32_32x32x16_bf16 v[82:97], v[220:223], v[142:145], v[82:97]
	v_mfma_f32_32x32x16_bf16 v[66:81], v[224:227], v[142:145], v[66:81]
	s_cmp_gt_u32 s87, s64
	s_cselect_b64 s[80:81], -1, 0
	s_and_b64 s[10:11], s[48:49], s[80:81]
	s_andn2_b64 vcc, exec, s[10:11]
	s_mov_b64 s[72:73], s[84:85]
	s_cbranch_vccnz .LBB0_535
	global_load_dwordx4 v[98:101], v[186:187], off
	global_load_dwordx4 v[102:105], v[186:187], off offset:32
	global_load_dwordx4 v[106:109], v[186:187], off offset:64
	global_load_dwordx4 v[110:113], v[186:187], off offset:96
	global_load_dwordx4 v[114:117], v[186:187], off offset:128
	global_load_dwordx4 v[118:121], v[186:187], off offset:160
	global_load_dwordx4 v[122:125], v[186:187], off offset:192
	global_load_dwordx4 v[126:129], v[186:187], off offset:224
	global_load_dwordx4 v[130:133], v[186:187], off offset:256
	global_load_dwordx4 v[134:137], v[186:187], off offset:288
	global_load_dwordx4 v[138:141], v[186:187], off offset:320
	global_load_dwordx4 v[142:145], v[186:187], off offset:352
	s_mov_b64 s[72:73], -1
.LBB0_535:
	s_sub_i32 s101, s86, 94
	s_cmp_gt_i32 s101, s65
	s_cbranch_scc0 .Lnoskip2
	s_nop 7
	s_nop 4
	v_mov_b32_e32 v66, 0
	v_mov_b32_e32 v67, 0
	v_mov_b32_e32 v68, 0
	v_mov_b32_e32 v69, 0
	v_mov_b32_e32 v70, 0
	v_mov_b32_e32 v71, 0
	v_mov_b32_e32 v72, 0
	v_mov_b32_e32 v73, 0
	v_mov_b32_e32 v74, 0
	v_mov_b32_e32 v75, 0
	v_mov_b32_e32 v76, 0
	v_mov_b32_e32 v77, 0
	v_mov_b32_e32 v78, 0
	v_mov_b32_e32 v79, 0
	v_mov_b32_e32 v80, 0
	v_mov_b32_e32 v81, 0
	v_mov_b32_e32 v88, 0
	v_mov_b32_e32 v89, 0
	v_mov_b32_e32 v216, 1.0
	s_branch .LBB0_541

.LBB0_556:
.LBB0_557:
	s_lshl_b32 s10, s25, 14
	v_add_u32_e32 v0, s10, v195
	ds_read_b64_tr_b16 v[82:83], v0 offset:0
	ds_read_b64_tr_b16 v[84:85], v0 offset:0x800
	ds_read_b64_tr_b16 v[90:91], v0 offset:0x1000
	ds_read_b64_tr_b16 v[92:93], v0 offset:0x1800
	ds_read_b64_tr_b16 v[94:95], v0 offset:0x2000
	ds_read_b64_tr_b16 v[96:97], v0 offset:0x2800
	ds_read_b64_tr_b16 v[146:147], v0 offset:0x3000
	ds_read_b64_tr_b16 v[148:149], v0 offset:0x3800
	ds_read_b64_tr_b16 v[150:151], v0 offset:0x200
	ds_read_b64_tr_b16 v[152:153], v0 offset:0xa00
	ds_read_b64_tr_b16 v[154:155], v0 offset:0x1200
	ds_read_b64_tr_b16 v[156:157], v0 offset:0x1a00
	ds_read_b64_tr_b16 v[218:219], v0 offset:0x2200
	ds_read_b64_tr_b16 v[220:221], v0 offset:0x2a00
	ds_read_b64_tr_b16 v[222:223], v0 offset:0x3200
	ds_read_b64_tr_b16 v[224:225], v0 offset:0x3a00
	s_waitcnt lgkmcnt(8)
	v_mfma_f32_32x32x16_bf16 v[50:65], v[66:69], v[82:85], v[50:65]
	v_mfma_f32_32x32x16_bf16 v[50:65], v[70:73], v[90:93], v[50:65]
	v_mfma_f32_32x32x16_bf16 v[50:65], v[74:77], v[94:97], v[50:65]
	v_mfma_f32_32x32x16_bf16 v[50:65], v[78:81], v[146:149], v[50:65]
	ds_read_b64_tr_b16 v[82:83], v0 offset:0x400
	ds_read_b64_tr_b16 v[84:85], v0 offset:0xc00
	ds_read_b64_tr_b16 v[90:91], v0 offset:0x1400
	ds_read_b64_tr_b16 v[92:93], v0 offset:0x1c00
	ds_read_b64_tr_b16 v[94:95], v0 offset:0x2400
	ds_read_b64_tr_b16 v[96:97], v0 offset:0x2c00
	ds_read_b64_tr_b16 v[146:147], v0 offset:0x3400
	ds_read_b64_tr_b16 v[148:149], v0 offset:0x3c00
	s_waitcnt lgkmcnt(8)
	v_mfma_f32_32x32x16_bf16 v[34:49], v[66:69], v[150:153], v[34:49]
	v_mfma_f32_32x32x16_bf16 v[34:49], v[70:73], v[154:157], v[34:49]
	v_mfma_f32_32x32x16_bf16 v[34:49], v[74:77], v[218:221], v[34:49]
	v_mfma_f32_32x32x16_bf16 v[34:49], v[78:81], v[222:225], v[34:49]
	ds_read_b64_tr_b16 v[150:151], v0 offset:0x600
	ds_read_b64_tr_b16 v[152:153], v0 offset:0xe00
	ds_read_b64_tr_b16 v[154:155], v0 offset:0x1600
	ds_read_b64_tr_b16 v[156:157], v0 offset:0x1e00
	ds_read_b64_tr_b16 v[218:219], v0 offset:0x2600
	ds_read_b64_tr_b16 v[220:221], v0 offset:0x2e00
	ds_read_b64_tr_b16 v[222:223], v0 offset:0x3600
	ds_read_b64_tr_b16 v[224:225], v0 offset:0x3e00
	s_waitcnt lgkmcnt(8)
	v_mfma_f32_32x32x16_bf16 v[18:33], v[66:69], v[82:85], v[18:33]
	v_mfma_f32_32x32x16_bf16 v[18:33], v[70:73], v[90:93], v[18:33]
	v_mfma_f32_32x32x16_bf16 v[18:33], v[74:77], v[94:97], v[18:33]
	v_mfma_f32_32x32x16_bf16 v[18:33], v[78:81], v[146:149], v[18:33]
	s_waitcnt lgkmcnt(0)
	v_mfma_f32_32x32x16_bf16 v[2:17], v[66:69], v[150:153], v[2:17]
	v_mfma_f32_32x32x16_bf16 v[2:17], v[70:73], v[154:157], v[2:17]
	v_mfma_f32_32x32x16_bf16 v[2:17], v[74:77], v[218:221], v[2:17]
	v_mfma_f32_32x32x16_bf16 v[2:17], v[78:81], v[222:225], v[2:17]
	s_andn2_b64 vcc, exec, s[36:37]
	s_cbranch_vccnz .LBB0_567
	s_andn2_b64 vcc, exec, s[82:83]
	s_cbranch_vccnz .LBB0_564
	s_xor_b64 s[18:19], s[72:73], -1
	s_mov_b64 s[4:5], -1
	s_and_b64 vcc, exec, s[18:19]
	s_cbranch_vccz .LBB0_561
	s_waitcnt vmcnt(0)
	s_mov_b64 s[4:5], 0

.LBB0_710:
	s_setprio 0
	v_readlane_b32 s4, v244, 27
	v_readlane_b32 s5, v244, 28
	s_cmp_gt_i32 s5, 4
	s_cselect_b64 s[0:1], -1, 0
	s_and_b64 s[4:5], s[22:23], s[0:1]
	s_andn2_b64 vcc, exec, s[4:5]
	v_readlane_b32 s6, v244, 29
	v_readlane_b32 s7, v244, 30
	s_cbranch_vccnz .LBB0_760
	s_waitcnt vmcnt(0)
	v_cmp_eq_u32_e32 vcc, 0, v209
	s_waitcnt vmcnt(0) lgkmcnt(0)
	s_barrier
	s_and_saveexec_b64 s[4:5], vcc
	s_cbranch_execz .LBB0_759
	s_add_i32 s3, 0, 0x20000
	v_mov_b32_e32 v0, s3
	s_waitcnt vmcnt(0) expcnt(0) lgkmcnt(0)
	ds_read_b32 v2, v0
	s_add_i32 s3, 0, 0x20004
	v_mov_b32_e32 v0, s3
	ds_read_b32 v0, v0
	s_waitcnt lgkmcnt(1)
	v_cmp_ne_u32_e32 vcc, 0, v2
	s_cbranch_vccnz .LBB0_727
	v_readlane_b32 s8, v244, 27
	v_readlane_b32 s11, v244, 30
	s_add_u32 s6, s58, 0x1000
	v_readlane_b32 s10, v244, 29
	s_mul_i32 s3, s11, s97
	s_addc_u32 s7, s59, 0
	s_mul_i32 s3, s3, s10
	s_add_u32 s10, s58, 0x1100
	s_addc_u32 s11, s59, 0
	s_add_u32 s18, s58, 0x1200
	s_addc_u32 s19, s59, 0
	s_add_u32 s22, s58, 0x1300
	s_addc_u32 s23, s59, 0
	s_mov_b32 s34, 1
	v_mov_b32_e32 v16, 0
	v_readlane_b32 s9, v244, 28
	s_branch .LBB0_715

.LBB0_961:
	ds_read_b128 v[144:147], v155
	ds_read_b128 v[148:151], v155 offset:1024
	ds_read_b128 v[158:161], v155 offset:2048
	ds_read_b128 v[162:165], v155 offset:3072
	ds_read_b128 v[166:169], v156
	ds_read_b128 v[170:173], v156 offset:1024
	ds_read_b128 v[174:177], v156 offset:2048
	ds_read_b128 v[178:181], v156 offset:3072
	s_add_i32 s78, s10, 2
	s_add_u32 s33, s46, 0x80
	s_addc_u32 s11, s47, 0
	s_cmp_eq_u32 s65, s10
	s_cselect_b32 s10, s4, s33
	s_cselect_b32 s11, s5, s11
	s_cselect_b32 s81, s45, s49
	s_cselect_b32 s80, s44, s48
	v_lshl_add_u64 v[218:219], s[46:47], 0, v[136:137]
	s_add_i32 m0, s35, 0xc000
	ds_read_b128 v[182:185], v157
	ds_read_b128 v[186:189], v157 offset:1024
	ds_read_b128 v[190:193], v157 offset:2048
	ds_read_b128 v[194:197], v157 offset:3072
	ds_read_b128 v[198:201], v157 offset:4096
	ds_read_b128 v[204:207], v157 offset:5120
	ds_read_b128 v[210:213], v157 offset:6144
	ds_read_b128 v[214:217], v157 offset:7168
	global_load_lds_dwordx4 v[218:219], off
	v_lshl_add_u64 v[218:219], s[46:47], 0, v[138:139]
	s_add_i32 m0, s35, 0xe000
	s_nop 0
	global_load_lds_dwordx4 v[218:219], off
	s_waitcnt vmcnt(8)
	s_waitcnt lgkmcnt(0)
	s_barrier
	s_setprio 1
	s_waitcnt lgkmcnt(0)
	v_mfma_f32_16x16x32_bf16 v[124:127], v[144:147], v[182:185], v[124:127]
	v_mfma_f32_16x16x32_bf16 v[120:123], v[158:161], v[182:185], v[120:123]
	v_mfma_f32_16x16x32_bf16 v[116:119], v[144:147], v[190:193], v[116:119]
	v_mfma_f32_16x16x32_bf16 v[108:111], v[158:161], v[190:193], v[108:111]
	v_mfma_f32_16x16x32_bf16 v[100:103], v[144:147], v[198:201], v[100:103]
	v_mfma_f32_16x16x32_bf16 v[92:95], v[158:161], v[198:201], v[92:95]
	v_mfma_f32_16x16x32_bf16 v[84:87], v[144:147], v[210:213], v[84:87]
	v_mfma_f32_16x16x32_bf16 v[76:79], v[158:161], v[210:213], v[76:79]
	v_mfma_f32_16x16x32_bf16 v[124:127], v[148:151], v[186:189], v[124:127]
	v_mfma_f32_16x16x32_bf16 v[120:123], v[162:165], v[186:189], v[120:123]
	v_mfma_f32_16x16x32_bf16 v[116:119], v[148:151], v[194:197], v[116:119]
	v_mfma_f32_16x16x32_bf16 v[108:111], v[162:165], v[194:197], v[108:111]
	v_mfma_f32_16x16x32_bf16 v[100:103], v[148:151], v[204:207], v[100:103]
	v_mfma_f32_16x16x32_bf16 v[92:95], v[162:165], v[204:207], v[92:95]
	v_mfma_f32_16x16x32_bf16 v[84:87], v[148:151], v[214:217], v[84:87]
	v_mfma_f32_16x16x32_bf16 v[76:79], v[162:165], v[214:217], v[76:79]
	s_setprio 0
	s_setprio 1
	v_mfma_f32_16x16x32_bf16 v[112:115], v[166:169], v[182:185], v[112:115]
	v_mfma_f32_16x16x32_bf16 v[104:107], v[174:177], v[182:185], v[104:107]
	v_mfma_f32_16x16x32_bf16 v[96:99], v[166:169], v[190:193], v[96:99]
	v_mfma_f32_16x16x32_bf16 v[88:91], v[174:177], v[190:193], v[88:91]
	v_mfma_f32_16x16x32_bf16 v[80:83], v[166:169], v[198:201], v[80:83]
	v_mfma_f32_16x16x32_bf16 v[72:75], v[174:177], v[198:201], v[72:75]
	v_mfma_f32_16x16x32_bf16 v[68:71], v[166:169], v[210:213], v[68:71]
	v_mfma_f32_16x16x32_bf16 v[64:67], v[174:177], v[210:213], v[64:67]
	v_mfma_f32_16x16x32_bf16 v[112:115], v[170:173], v[186:189], v[112:115]
	v_mfma_f32_16x16x32_bf16 v[104:107], v[178:181], v[186:189], v[104:107]
	v_mfma_f32_16x16x32_bf16 v[96:99], v[170:173], v[194:197], v[96:99]
	v_mfma_f32_16x16x32_bf16 v[88:91], v[178:181], v[194:197], v[88:91]
	v_mfma_f32_16x16x32_bf16 v[80:83], v[170:173], v[204:207], v[80:83]
	v_mfma_f32_16x16x32_bf16 v[72:75], v[178:181], v[204:207], v[72:75]
	v_mfma_f32_16x16x32_bf16 v[68:71], v[170:173], v[214:217], v[68:71]
	v_mfma_f32_16x16x32_bf16 v[64:67], v[178:181], v[214:217], v[64:67]
	s_setprio 0
	s_barrier
	s_add_i32 s33, s68, s34
	v_lshl_add_u64 v[218:219], s[80:81], 0, v[130:131]
	s_mov_b32 m0, s33
	ds_read_b128 v[182:185], v157 offset:16384
	ds_read_b128 v[186:189], v157 offset:17408
	ds_read_b128 v[190:193], v157 offset:18432
	ds_read_b128 v[194:197], v157 offset:19456
	ds_read_b128 v[198:201], v157 offset:20480
	ds_read_b128 v[204:207], v157 offset:21504
	ds_read_b128 v[210:213], v157 offset:22528
	ds_read_b128 v[214:217], v157 offset:23552
	global_load_lds_dwordx4 v[218:219], off
	s_add_i32 m0, s33, 0x2000
	v_lshl_add_u64 v[220:221], s[80:81], 0, v[134:135]
	s_add_u32 s80, s80, s16
	s_addc_u32 s81, s81, s17
	s_add_i32 s33, s69, s34
	global_load_lds_dwordx4 v[220:221], off
	v_lshl_add_u64 v[222:223], s[80:81], 0, v[130:131]
	s_mov_b32 m0, s33
	v_lshl_add_u64 v[224:225], s[80:81], 0, v[134:135]
	global_load_lds_dwordx4 v[222:223], off
	s_add_i32 m0, s33, 0x2000
	v_lshl_add_u64 v[226:227], s[10:11], 0, v[128:129]
	global_load_lds_dwordx4 v[224:225], off
	s_mov_b32 m0, s35
	v_lshl_add_u64 v[228:229], s[10:11], 0, v[132:133]
	global_load_lds_dwordx4 v[226:227], off
	s_mov_b32 m0, s50
	s_nop 0
	global_load_lds_dwordx4 v[228:229], off
	s_waitcnt vmcnt(8)
	s_waitcnt lgkmcnt(0)
	s_barrier
	s_setprio 1
	s_waitcnt lgkmcnt(0)
	v_mfma_f32_16x16x32_bf16 v[60:63], v[144:147], v[182:185], v[60:63]
	v_mfma_f32_16x16x32_bf16 v[56:59], v[158:161], v[182:185], v[56:59]
	v_mfma_f32_16x16x32_bf16 v[52:55], v[144:147], v[190:193], v[52:55]
	v_mfma_f32_16x16x32_bf16 v[44:47], v[158:161], v[190:193], v[44:47]
	v_mfma_f32_16x16x32_bf16 v[36:39], v[144:147], v[198:201], v[36:39]
	v_mfma_f32_16x16x32_bf16 v[28:31], v[158:161], v[198:201], v[28:31]
	v_mfma_f32_16x16x32_bf16 v[20:23], v[144:147], v[210:213], v[20:23]
	v_mfma_f32_16x16x32_bf16 v[12:15], v[158:161], v[210:213], v[12:15]
	v_mfma_f32_16x16x32_bf16 v[60:63], v[148:151], v[186:189], v[60:63]
	v_mfma_f32_16x16x32_bf16 v[56:59], v[162:165], v[186:189], v[56:59]
	v_mfma_f32_16x16x32_bf16 v[52:55], v[148:151], v[194:197], v[52:55]
	v_mfma_f32_16x16x32_bf16 v[44:47], v[162:165], v[194:197], v[44:47]
	v_mfma_f32_16x16x32_bf16 v[36:39], v[148:151], v[204:207], v[36:39]
	v_mfma_f32_16x16x32_bf16 v[28:31], v[162:165], v[204:207], v[28:31]
	v_mfma_f32_16x16x32_bf16 v[20:23], v[148:151], v[214:217], v[20:23]
	v_mfma_f32_16x16x32_bf16 v[12:15], v[162:165], v[214:217], v[12:15]
	s_setprio 0
	s_setprio 1
	v_mfma_f32_16x16x32_bf16 v[48:51], v[166:169], v[182:185], v[48:51]
	v_mfma_f32_16x16x32_bf16 v[40:43], v[174:177], v[182:185], v[40:43]
	v_mfma_f32_16x16x32_bf16 v[32:35], v[166:169], v[190:193], v[32:35]
	v_mfma_f32_16x16x32_bf16 v[24:27], v[174:177], v[190:193], v[24:27]
	v_mfma_f32_16x16x32_bf16 v[16:19], v[166:169], v[198:201], v[16:19]
	v_mfma_f32_16x16x32_bf16 v[8:11], v[174:177], v[198:201], v[8:11]
	v_mfma_f32_16x16x32_bf16 v[4:7], v[166:169], v[210:213], v[4:7]
	v_mfma_f32_16x16x32_bf16 v[0:3], v[174:177], v[210:213], v[0:3]
	v_mfma_f32_16x16x32_bf16 v[48:51], v[170:173], v[186:189], v[48:51]
	v_mfma_f32_16x16x32_bf16 v[40:43], v[178:181], v[186:189], v[40:43]
	v_mfma_f32_16x16x32_bf16 v[32:35], v[170:173], v[194:197], v[32:35]
	v_mfma_f32_16x16x32_bf16 v[24:27], v[178:181], v[194:197], v[24:27]
	v_mfma_f32_16x16x32_bf16 v[16:19], v[170:173], v[204:207], v[16:19]
	v_mfma_f32_16x16x32_bf16 v[8:11], v[178:181], v[204:207], v[8:11]
	v_mfma_f32_16x16x32_bf16 v[4:7], v[170:173], v[214:217], v[4:7]
	v_mfma_f32_16x16x32_bf16 v[0:3], v[178:181], v[214:217], v[0:3]
	s_setprio 0
	s_barrier
	s_add_i32 s33, 0, 0x18000
	s_add_i32 s79, 0, 0x1c000
	v_add_u32_e32 v162, s33, v153
	v_add_u32_e32 v178, s79, v153
	ds_read_b128 v[144:147], v162
	ds_read_b128 v[148:151], v162 offset:1024
	ds_read_b128 v[158:161], v162 offset:2048
	ds_read_b128 v[162:165], v162 offset:3072
	ds_read_b128 v[166:169], v178
	ds_read_b128 v[170:173], v178 offset:1024
	ds_read_b128 v[174:177], v178 offset:2048
	ds_read_b128 v[178:181], v178 offset:3072
	s_add_u32 s10, s10, s16
	s_addc_u32 s11, s11, s17
	s_mov_b32 m0, s51
	v_lshl_add_u64 v[230:231], s[10:11], 0, v[128:129]
	ds_read_b128 v[182:185], v157 offset:32768
	ds_read_b128 v[186:189], v157 offset:33792
	ds_read_b128 v[190:193], v157 offset:34816
	ds_read_b128 v[194:197], v157 offset:35840
	ds_read_b128 v[198:201], v157 offset:36864
	ds_read_b128 v[204:207], v157 offset:37888
	ds_read_b128 v[210:213], v157 offset:38912
	ds_read_b128 v[214:217], v157 offset:39936
	global_load_lds_dwordx4 v[230:231], off
	v_lshl_add_u64 v[230:231], s[10:11], 0, v[132:133]
	s_mov_b32 m0, s52
	s_nop 0
	global_load_lds_dwordx4 v[230:231], off
	s_waitcnt vmcnt(8)
	s_waitcnt lgkmcnt(0)
	s_barrier
	s_setprio 1
	s_waitcnt lgkmcnt(0)
	v_mfma_f32_16x16x32_bf16 v[124:127], v[144:147], v[182:185], v[124:127]
	v_mfma_f32_16x16x32_bf16 v[120:123], v[158:161], v[182:185], v[120:123]
	v_mfma_f32_16x16x32_bf16 v[116:119], v[144:147], v[190:193], v[116:119]
	v_mfma_f32_16x16x32_bf16 v[108:111], v[158:161], v[190:193], v[108:111]
	v_mfma_f32_16x16x32_bf16 v[100:103], v[144:147], v[198:201], v[100:103]
	v_mfma_f32_16x16x32_bf16 v[92:95], v[158:161], v[198:201], v[92:95]
	v_mfma_f32_16x16x32_bf16 v[84:87], v[144:147], v[210:213], v[84:87]
	v_mfma_f32_16x16x32_bf16 v[76:79], v[158:161], v[210:213], v[76:79]
	v_mfma_f32_16x16x32_bf16 v[124:127], v[148:151], v[186:189], v[124:127]
	v_mfma_f32_16x16x32_bf16 v[120:123], v[162:165], v[186:189], v[120:123]
	v_mfma_f32_16x16x32_bf16 v[116:119], v[148:151], v[194:197], v[116:119]
	v_mfma_f32_16x16x32_bf16 v[108:111], v[162:165], v[194:197], v[108:111]
	v_mfma_f32_16x16x32_bf16 v[100:103], v[148:151], v[204:207], v[100:103]
	v_mfma_f32_16x16x32_bf16 v[92:95], v[162:165], v[204:207], v[92:95]
	v_mfma_f32_16x16x32_bf16 v[84:87], v[148:151], v[214:217], v[84:87]
	v_mfma_f32_16x16x32_bf16 v[76:79], v[162:165], v[214:217], v[76:79]
	s_setprio 0
	s_setprio 1
	v_mfma_f32_16x16x32_bf16 v[112:115], v[166:169], v[182:185], v[112:115]
	v_mfma_f32_16x16x32_bf16 v[104:107], v[174:177], v[182:185], v[104:107]
	v_mfma_f32_16x16x32_bf16 v[96:99], v[166:169], v[190:193], v[96:99]
	v_mfma_f32_16x16x32_bf16 v[88:91], v[174:177], v[190:193], v[88:91]
	v_mfma_f32_16x16x32_bf16 v[80:83], v[166:169], v[198:201], v[80:83]
	v_mfma_f32_16x16x32_bf16 v[72:75], v[174:177], v[198:201], v[72:75]
	v_mfma_f32_16x16x32_bf16 v[68:71], v[166:169], v[210:213], v[68:71]
	v_mfma_f32_16x16x32_bf16 v[64:67], v[174:177], v[210:213], v[64:67]
	v_mfma_f32_16x16x32_bf16 v[112:115], v[170:173], v[186:189], v[112:115]
	v_mfma_f32_16x16x32_bf16 v[104:107], v[178:181], v[186:189], v[104:107]
	v_mfma_f32_16x16x32_bf16 v[96:99], v[170:173], v[194:197], v[96:99]
	v_mfma_f32_16x16x32_bf16 v[88:91], v[178:181], v[194:197], v[88:91]
	v_mfma_f32_16x16x32_bf16 v[80:83], v[170:173], v[204:207], v[80:83]
	v_mfma_f32_16x16x32_bf16 v[72:75], v[178:181], v[204:207], v[72:75]
	v_mfma_f32_16x16x32_bf16 v[68:71], v[170:173], v[214:217], v[68:71]
	v_mfma_f32_16x16x32_bf16 v[64:67], v[178:181], v[214:217], v[64:67]
	s_setprio 0
	s_barrier
	s_add_i32 s10, s33, s34
	v_lshl_add_u64 v[218:219], v[218:219], 0, s[22:23]
	s_mov_b32 m0, s10
	ds_read_b128 v[182:185], v157 offset:49152
	ds_read_b128 v[186:189], v157 offset:50176
	ds_read_b128 v[190:193], v157 offset:51200
	ds_read_b128 v[194:197], v157 offset:52224
	ds_read_b128 v[198:201], v157 offset:53248
	ds_read_b128 v[204:207], v157 offset:54272
	ds_read_b128 v[210:213], v157 offset:55296
	ds_read_b128 v[214:217], v157 offset:56320
	global_load_lds_dwordx4 v[218:219], off
	v_lshl_add_u64 v[218:219], v[220:221], 0, s[22:23]
	s_add_i32 m0, s10, 0x2000
	s_add_i32 s10, s79, s34
	global_load_lds_dwordx4 v[218:219], off
	v_lshl_add_u64 v[218:219], v[222:223], 0, s[22:23]
	s_mov_b32 m0, s10
	s_nop 0
	global_load_lds_dwordx4 v[218:219], off
	v_lshl_add_u64 v[218:219], v[224:225], 0, s[22:23]
	s_add_i32 m0, s10, 0x2000
	s_nop 0
	global_load_lds_dwordx4 v[218:219], off
	v_lshl_add_u64 v[218:219], v[226:227], 0, s[22:23]
	s_mov_b32 m0, s62
	s_nop 0
	global_load_lds_dwordx4 v[218:219], off
	v_lshl_add_u64 v[218:219], v[228:229], 0, s[22:23]
	s_mov_b32 m0, s63
	s_nop 0
	global_load_lds_dwordx4 v[218:219], off
	s_waitcnt vmcnt(8)
	s_waitcnt lgkmcnt(0)
	s_barrier
	s_setprio 1
	s_waitcnt lgkmcnt(0)
	v_mfma_f32_16x16x32_bf16 v[60:63], v[144:147], v[182:185], v[60:63]
	v_mfma_f32_16x16x32_bf16 v[56:59], v[158:161], v[182:185], v[56:59]
	v_mfma_f32_16x16x32_bf16 v[52:55], v[144:147], v[190:193], v[52:55]
	v_mfma_f32_16x16x32_bf16 v[44:47], v[158:161], v[190:193], v[44:47]
	v_mfma_f32_16x16x32_bf16 v[36:39], v[144:147], v[198:201], v[36:39]
	v_mfma_f32_16x16x32_bf16 v[28:31], v[158:161], v[198:201], v[28:31]
	v_mfma_f32_16x16x32_bf16 v[20:23], v[144:147], v[210:213], v[20:23]
	v_mfma_f32_16x16x32_bf16 v[12:15], v[158:161], v[210:213], v[12:15]
	v_mfma_f32_16x16x32_bf16 v[60:63], v[148:151], v[186:189], v[60:63]
	v_mfma_f32_16x16x32_bf16 v[56:59], v[162:165], v[186:189], v[56:59]
	v_mfma_f32_16x16x32_bf16 v[52:55], v[148:151], v[194:197], v[52:55]
	v_mfma_f32_16x16x32_bf16 v[44:47], v[162:165], v[194:197], v[44:47]
	v_mfma_f32_16x16x32_bf16 v[36:39], v[148:151], v[204:207], v[36:39]
	v_mfma_f32_16x16x32_bf16 v[28:31], v[162:165], v[204:207], v[28:31]
	v_mfma_f32_16x16x32_bf16 v[20:23], v[148:151], v[214:217], v[20:23]
	v_mfma_f32_16x16x32_bf16 v[12:15], v[162:165], v[214:217], v[12:15]
	s_setprio 0
	s_setprio 1
	v_mfma_f32_16x16x32_bf16 v[48:51], v[166:169], v[182:185], v[48:51]
	v_mfma_f32_16x16x32_bf16 v[40:43], v[174:177], v[182:185], v[40:43]
	v_mfma_f32_16x16x32_bf16 v[32:35], v[166:169], v[190:193], v[32:35]
	v_mfma_f32_16x16x32_bf16 v[24:27], v[174:177], v[190:193], v[24:27]
	v_mfma_f32_16x16x32_bf16 v[16:19], v[166:169], v[198:201], v[16:19]
	v_mfma_f32_16x16x32_bf16 v[8:11], v[174:177], v[198:201], v[8:11]
	v_mfma_f32_16x16x32_bf16 v[4:7], v[166:169], v[210:213], v[4:7]
	v_mfma_f32_16x16x32_bf16 v[0:3], v[174:177], v[210:213], v[0:3]
	v_mfma_f32_16x16x32_bf16 v[48:51], v[170:173], v[186:189], v[48:51]
	v_mfma_f32_16x16x32_bf16 v[40:43], v[178:181], v[186:189], v[40:43]
	v_mfma_f32_16x16x32_bf16 v[32:35], v[170:173], v[194:197], v[32:35]
	v_mfma_f32_16x16x32_bf16 v[24:27], v[178:181], v[194:197], v[24:27]
	v_mfma_f32_16x16x32_bf16 v[16:19], v[170:173], v[204:207], v[16:19]
	v_mfma_f32_16x16x32_bf16 v[8:11], v[178:181], v[204:207], v[8:11]
	v_mfma_f32_16x16x32_bf16 v[4:7], v[170:173], v[214:217], v[4:7]
	v_mfma_f32_16x16x32_bf16 v[0:3], v[178:181], v[214:217], v[0:3]
	s_setprio 0
	s_barrier
	s_add_u32 s46, s46, 0x100
	s_addc_u32 s47, s47, 0
	s_add_u32 s48, s48, 0x100
	s_addc_u32 s49, s49, 0
	s_cmp_ge_i32 s78, s64
	s_mov_b32 s10, s78
	s_cbranch_scc0 .LBB0_961
	v_max_f32_e32 v144, 0, v112
	v_max_f32_e32 v145, 0, v113
	v_max_f32_e32 v146, 0, v114
	v_max_f32_e32 v147, 0, v115
	v_max_f32_e32 v113, 0, v97
	v_max_f32_e32 v114, 0, v98
	v_max_f32_e32 v148, 0, v104
	v_max_f32_e32 v115, 0, v99
	v_max_f32_e32 v149, 0, v105
	v_max_f32_e32 v97, 0, v73
	v_max_f32_e32 v150, 0, v106
	v_max_f32_e32 v98, 0, v74
	v_max_f32_e32 v151, 0, v107
	v_max_f32_e32 v99, 0, v75
	v_max_f32_e32 v105, 0, v117
	v_max_f32_e32 v117, 0, v89
	v_max_f32_e32 v73, 0, v85
	v_max_f32_e32 v85, 0, v49
	v_max_f32_e32 v106, 0, v118
	v_max_f32_e32 v118, 0, v90
	v_max_f32_e32 v74, 0, v86
	v_max_f32_e32 v86, 0, v50
	v_max_f32_e32 v107, 0, v119
	v_max_f32_e32 v119, 0, v91
	v_max_f32_e32 v75, 0, v87
	v_max_f32_e32 v87, 0, v51
	v_max_f32_e32 v89, 0, v101
	v_max_f32_e32 v101, 0, v41
	v_max_f32_e32 v49, 0, v33
	v_max_f32_e32 v90, 0, v102
	v_max_f32_e32 v102, 0, v42
	v_max_f32_e32 v50, 0, v34
	v_max_f32_e32 v91, 0, v103
	v_max_f32_e32 v103, 0, v43
	v_max_f32_e32 v51, 0, v35
	v_max_f32_e32 v41, 0, v53
	v_max_f32_e32 v53, 0, v25
	v_max_f32_e32 v33, 0, v9
	v_max_f32_e32 v42, 0, v54
	v_max_f32_e32 v54, 0, v26
	v_max_f32_e32 v34, 0, v10
	v_max_f32_e32 v124, 0, v124
	v_max_f32_e32 v125, 0, v125
	v_max_f32_e32 v126, 0, v126
	v_max_f32_e32 v127, 0, v127
	v_max_f32_e32 v120, 0, v120
	v_max_f32_e32 v121, 0, v121
	v_max_f32_e32 v122, 0, v122
	v_max_f32_e32 v123, 0, v123
	v_max_f32_e32 v108, 0, v108
	v_max_f32_e32 v109, 0, v109
	v_max_f32_e32 v110, 0, v110
	v_max_f32_e32 v111, 0, v111
	v_max_f32_e32 v92, 0, v92
	v_max_f32_e32 v93, 0, v93
	v_max_f32_e32 v94, 0, v94
	v_max_f32_e32 v95, 0, v95
	v_max_f32_e32 v80, 0, v80
	v_max_f32_e32 v81, 0, v81
	v_max_f32_e32 v82, 0, v82
	v_max_f32_e32 v83, 0, v83
	v_max_f32_e32 v76, 0, v76
	v_max_f32_e32 v77, 0, v77
	v_max_f32_e32 v78, 0, v78
	v_max_f32_e32 v79, 0, v79
	v_max_f32_e32 v68, 0, v68
	v_max_f32_e32 v69, 0, v69
	v_max_f32_e32 v70, 0, v70
	v_max_f32_e32 v71, 0, v71
	v_max_f32_e32 v64, 0, v64
	v_max_f32_e32 v65, 0, v65
	v_max_f32_e32 v66, 0, v66
	v_max_f32_e32 v67, 0, v67
	v_max_f32_e32 v60, 0, v60
	v_max_f32_e32 v61, 0, v61
	v_max_f32_e32 v62, 0, v62
	v_max_f32_e32 v63, 0, v63
	v_max_f32_e32 v56, 0, v56
	v_max_f32_e32 v57, 0, v57
	v_max_f32_e32 v58, 0, v58
	v_max_f32_e32 v59, 0, v59
	v_max_f32_e32 v43, 0, v55
	v_max_f32_e32 v44, 0, v44
	v_max_f32_e32 v45, 0, v45
	v_max_f32_e32 v46, 0, v46
	v_max_f32_e32 v47, 0, v47
	v_max_f32_e32 v55, 0, v27
	v_max_f32_e32 v25, 0, v37
	v_max_f32_e32 v26, 0, v38
	v_max_f32_e32 v27, 0, v39
	v_max_f32_e32 v28, 0, v28
	v_max_f32_e32 v29, 0, v29
	v_max_f32_e32 v30, 0, v30
	v_max_f32_e32 v31, 0, v31
	v_max_f32_e32 v16, 0, v16
	v_max_f32_e32 v17, 0, v17
	v_max_f32_e32 v18, 0, v18
	v_max_f32_e32 v19, 0, v19
	v_max_f32_e32 v35, 0, v11
	v_max_f32_e32 v9, 0, v21
	v_max_f32_e32 v10, 0, v22
	v_max_f32_e32 v11, 0, v23
	v_max_f32_e32 v12, 0, v12
	v_max_f32_e32 v13, 0, v13
	v_max_f32_e32 v14, 0, v14
	v_max_f32_e32 v15, 0, v15
	v_max_f32_e32 v4, 0, v4
	v_max_f32_e32 v5, 0, v5
	v_max_f32_e32 v6, 0, v6
	v_max_f32_e32 v7, 0, v7
	v_max_f32_e32 v0, 0, v0
	v_max_f32_e32 v1, 0, v1
	v_max_f32_e32 v2, 0, v2
	v_max_f32_e32 v3, 0, v3
	v_max_f32_e32 v112, 0, v96
	v_max_f32_e32 v96, 0, v72
	v_max_f32_e32 v104, 0, v116
	v_max_f32_e32 v72, 0, v84
	v_max_f32_e32 v116, 0, v88
	v_max_f32_e32 v84, 0, v48
	v_max_f32_e32 v88, 0, v100
	v_max_f32_e32 v48, 0, v32
	v_max_f32_e32 v32, 0, v8
	v_max_f32_e32 v100, 0, v40
	v_max_f32_e32 v8, 0, v20
	v_max_f32_e32 v40, 0, v52
	v_max_f32_e32 v52, 0, v24
	v_max_f32_e32 v24, 0, v36
